# CP: CO + deferred transposes chunks of 4 tiles (2560 chunks) instead of 8
# baseline (speedup 1.0000x reference)
; __global__ void __launch_bounds__(256, 2) fwd_megakernel(Params p) {
;     ...
;               if (l != 0 || rep != 0) break;
;               int j = atomicAdd((int*)(ws + OFF_CNT) + 16, 1);
;               if (j < TR_DEFER / TR_CHUNK) job = -2 - j;
;               break;
;             }
;           }
;           s_job = job;
.LBB0_696:
	s_andn2_saveexec_b64 s[4:5], s[10:11]
	s_cbranch_execz .LBB0_700
	v_readlane_b32 s10, v237, 29
	v_readlane_b32 s11, v237, 30
	v_mov_b32_e32 v3, -1
	s_andn2_b64 vcc, exec, s[10:11]
	s_cbranch_vccnz .LBB0_699
	v_readlane_b32 s10, v237, 23
	v_readlane_b32 s11, v237, 24
	s_movk_i32 s2, 0xa00
	s_nop 0
	v_mov_b64_e32 v[2:3], s[10:11]
	global_atomic_add v2, v[2:3], v198, off sc0
	s_waitcnt vmcnt(0) lgkmcnt(0)
	v_sub_u32_e32 v3, -2, v2
	v_cmp_gt_i32_e32 vcc, s2, v2
	s_nop 1
	v_cndmask_b32_e32 v3, -1, v3, vcc

; __device__ __forceinline__ TrJob tr_decode(const Params& p, char* ws, int job) {
;   TrJob t;
;   int l = job / TJ_PER_LAYER, rj = job % TJ_PER_LAYER;
;   if (rj < 640) {
;     t.src = p.w_in + (size_t)l * 1024 * 2560; t.K = 1024; t.N = 2560; t.kt = rj / 40; t.nt = rj % 40;
;     t.dst = (u16*)(ws + OFF_WINT) + (size_t)l * 2560 * 1024; t.mode = 0;
;   } else if (rj < 896) {
;     rj -= 640;
;     t.src = p.w_out + (size_t)l * 1024 * 1024; t.K = 1024; t.N = 1024; t.kt = rj / 16; t.nt = rj % 16;
;     t.dst = (u16*)(ws + OFF_WOUTT) + (size_t)l * 1024 * 1024; t.mode = 0;
;   } else {
;     rj -= 896;
;     int e = rj / 1536, q = rj % 1536;
;     size_t eo = (size_t)(l * 16 + e);
;     if (q < 512) {
;       t.src = p.w_gate + eo * 1024 * 2048; t.K = 1024; t.N = 2048; t.kt = q / 32; t.nt = q % 32;
;       t.dst = (u16*)(ws + OFF_WGUT) + eo * 4096 * 1024; t.mode = 1;
;     } else if (q < 1024) {
;       q -= 512;
;       t.src = p.w_up + eo * 1024 * 2048; t.K = 1024; t.N = 2048; t.kt = q / 32; t.nt = q % 32;
;       t.dst = (u16*)(ws + OFF_WGUT) + eo * 4096 * 1024; t.mode = 2;
;     } else {
;       q -= 1024;
;       t.src = p.w_down + eo * 2048 * 1024; t.K = 2048; t.N = 1024; t.kt = q / 16; t.nt = q % 16;
;       t.dst = (u16*)(ws + OFF_WDT) + eo * 1024 * 2048; t.mode = 0;
;     }
;   }
; __global__ void __launch_bounds__(256, 2) fwd_megakernel(Params p) {
;     ...
;         if (job < -1) {
;           const int c0_ = J_DEFER + (-2 - job) * TR_CHUNK;
;           p0_transposes(p, smem, 0, 1, c0_, c0_ + TR_CHUNK);
;           continue;
.LBB0_716:
	s_lshl_b32 s20, s10, 2
	s_sub_i32 s22, 0x9ef8, s20
	s_sub_i32 s2, 0x9efc, s20
	s_cmp_lt_i32 s22, s2
	v_mov_b32_e32 v2, v172
	s_mov_b64 s[0:1], s[58:59]
	s_cselect_b64 s[4:5], -1, 0
	s_cmp_ge_i32 s22, s2
	s_cbranch_scc1 .LBB0_750
	s_mul_hi_i32 s10, s22, 0x5254e78f
	s_lshr_b32 s11, s10, 31
	s_ashr_i32 s10, s10, 13
	s_add_i32 s10, s10, s11
	s_mul_i32 s11, s10, 0x6380
	s_sub_i32 s21, s22, s11
	s_cmpk_gt_i32 s21, 0x27f
	s_mov_b64 s[16:17], -1
	s_cbranch_scc0 .LBB0_731
	s_cmpk_gt_u32 s21, 0x37f
	s_cbranch_scc0 .LBB0_728
	s_add_i32 s11, s21, 0xfc80
	s_and_b32 s12, s11, 0xffff
	s_mul_i32 s12, s12, 0xaaab
	s_lshr_b32 s12, s12, 26
	s_mul_i32 s13, s12, 0x600
	s_sub_i32 s11, s11, s13
	s_and_b32 s24, s11, 0xffff
	s_lshl_b32 s11, s10, 4
	s_add_i32 s16, s11, s12
	s_ashr_i32 s17, s16, 31
	s_cmpk_gt_u32 s24, 0x1ff
	s_mov_b64 s[18:19], -1
	s_cbranch_scc0 .LBB0_725
	s_lshl_b64 s[18:19], s[16:17], 23
	s_cmpk_gt_u32 s24, 0x3ff
	s_mov_b64 s[14:15], -1
	s_cbranch_scc0 .LBB0_722
	v_readlane_b32 s40, v238, 25
	s_add_i32 s11, s24, 0xfffffc00
	v_readlane_b32 s46, v238, 31
	v_readlane_b32 s47, v238, 32
	s_add_u32 s12, s46, s18
	v_readlane_b32 s41, v238, 26
	v_readlane_b32 s42, v238, 27
	v_readlane_b32 s43, v238, 28
	v_readlane_b32 s44, v238, 29
	v_readlane_b32 s45, v238, 30
	s_addc_u32 s13, s47, s19
	s_lshr_b32 s23, s11, 4
	s_and_b32 s11, s24, 15
	s_mov_b64 s[14:15], 0

; __device__ __forceinline__ void tr_load(const Params& p, char* ws, int job, int tid, float4 (&r)[4]) {
;   TrJob t = tr_decode(p, ws, job);
;   const int c4 = tid & 15, rr = tid >> 4;
;   const float* s0 = t.src + (size_t)(t.kt * 64 + rr) * t.N + t.nt * 64 + c4 * 4;
; #pragma unroll
;   for (int pp = 0; pp < 4; ++pp) {
;     f32x4 v_ = __builtin_nontemporal_load((const f32x4*)(s0 + (size_t)(16 * pp) * t.N));
;     r[pp] = make_float4(v_[0], v_[1], v_[2], v_[3]);
;   }
; }
; __device__ __forceinline__ void p0_transposes(const Params& p, char* smem, int bid, int nb, int jlo, int jhi) {
;     ...
;   int j = jlo + bid * 2;
;   if (j < jhi) { tr_load(p, ws, j, tid, c0); tr_load(p, ws, j + 1, tid, c1); }
.LBB0_733:
	v_ashrrev_i32_e32 v3, 4, v2
	v_lshl_add_u32 v0, s23, 6, v3
	v_ashrrev_i32_e32 v4, 31, v0
	v_mul_lo_u32 v6, s14, v4
	v_mul_lo_u32 v7, s15, v0
	v_mad_u64_u32 v[4:5], s[16:17], s14, v0, 0
	v_add3_u32 v5, v5, v6, v7
	s_lshl_b32 s10, s11, 6
	v_lshlrev_b32_e32 v0, 2, v2
	v_lshl_add_u64 v[4:5], v[4:5], 2, s[12:13]
	s_ashr_i32 s11, s10, 31
	v_and_b32_e32 v0, 60, v0
	v_lshl_add_u64 v[4:5], s[10:11], 2, v[4:5]
	v_lshlrev_b32_e32 v0, 2, v0
	v_lshl_add_u64 v[4:5], v[4:5], 0, v[0:1]
	s_lshl_b64 s[10:11], s[14:15], 6
	v_lshl_add_u64 v[6:7], v[4:5], 0, s[10:11]
	global_load_dwordx4 v[18:21], v[4:5], off nt
	global_load_dwordx4 v[22:25], v[6:7], off nt
	v_lshl_add_u64 v[4:5], v[6:7], 0, s[10:11]
	v_lshl_add_u64 v[6:7], v[4:5], 0, s[10:11]
	global_load_dwordx4 v[26:29], v[4:5], off nt
	global_load_dwordx4 v[30:33], v[6:7], off nt
	s_sub_i32 s11, 0x9ef9, s20
	s_mul_hi_i32 s10, s11, 0x5254e78f
	s_lshr_b32 s12, s10, 31
	s_ashr_i32 s10, s10, 13
	s_add_i32 s10, s10, s12
	s_mul_i32 s12, s10, 0x6380
	s_sub_i32 s20, s11, s12
	s_cmpk_gt_i32 s20, 0x27f
	s_mov_b64 s[16:17], -1
	s_cbranch_scc0 .LBB0_747
	s_cmpk_gt_u32 s20, 0x37f
	s_cbranch_scc0 .LBB0_744
	s_add_i32 s11, s20, 0xfc80
	s_and_b32 s12, s11, 0xffff
	s_mul_i32 s12, s12, 0xaaab
	s_lshr_b32 s12, s12, 26
	s_mul_i32 s13, s12, 0x600
	s_sub_i32 s11, s11, s13
	s_and_b32 s23, s11, 0xffff
	s_lshl_b32 s11, s10, 4
	s_add_i32 s16, s11, s12
	s_ashr_i32 s17, s16, 31
	s_cmpk_gt_u32 s23, 0x1ff
	s_mov_b64 s[18:19], -1
	s_cbranch_scc0 .LBB0_741
	s_lshl_b64 s[18:19], s[16:17], 23
	s_cmpk_gt_u32 s23, 0x3ff
	s_mov_b64 s[14:15], -1
	s_cbranch_scc0 .LBB0_738
	v_readlane_b32 s24, v238, 25
	s_add_i32 s11, s23, 0xfffffc00
	v_readlane_b32 s30, v238, 31
	v_readlane_b32 s31, v238, 32
	s_add_u32 s12, s30, s18
	v_readlane_b32 s25, v238, 26
	v_readlane_b32 s26, v238, 27
	v_readlane_b32 s27, v238, 28
	v_readlane_b32 s28, v238, 29
	v_readlane_b32 s29, v238, 30
	s_addc_u32 s13, s31, s19
	s_lshr_b32 s21, s11, 4
	s_and_b32 s11, s23, 15
	s_mov_b64 s[14:15], 0
